# grid barriers: L1 invalidate issued at protocol entry instead of behind the release (on top of group barriers + remap + loop edits)
# speedup vs baseline: 1.0157x; 1.0049x over previous
.LBB0_202:
	v_readlane_b32 s2, v255, 0
	v_readlane_b32 s3, v255, 1
	s_cmp_eq_u32 s3, 1
	s_barrier
	s_cbranch_scc1 .LBB0_256
	s_mov_b64 s[6:7], s[0:1]
	s_mov_b32 s33, s90
	s_waitcnt vmcnt(0)
	v_cmp_eq_u32_e32 vcc, 0, v0
	s_barrier
	s_and_saveexec_b64 s[4:5], vcc
	s_cbranch_execz .LBB0_255
	buffer_inv sc1
	s_add_i32 s2, 0, 0x20000
	v_mov_b32_e32 v1, s2
	s_load_dwordx2 s[6:7], s[6:7], 0xd8
	s_waitcnt vmcnt(0) expcnt(0) lgkmcnt(0)
	ds_read_b32 v3, v1
	s_add_i32 s2, 0, 0x20004
	v_mov_b32_e32 v1, s2
	ds_read_b32 v1, v1
	s_waitcnt lgkmcnt(1)
	v_cmp_ne_u32_e32 vcc, 0, v3
	s_cbranch_vccnz .LBB0_219
	v_readlane_b32 s8, v255, 2
	v_readlane_b32 s9, v255, 3
	s_load_dwordx2 s[2:3], s[8:9], 0x4
	s_add_u32 s8, s6, 0x4200
	s_addc_u32 s9, s7, 0
	s_add_u32 s10, s6, 0x4400
	s_addc_u32 s11, s7, 0
	s_add_u32 s12, s6, 0x4500
	s_addc_u32 s13, s7, 0
	s_add_u32 s14, s6, 0x4600
	s_addc_u32 s15, s7, 0
	s_add_u32 s16, s6, 0x4700
	s_addc_u32 s17, s7, 0
	s_add_u32 s18, s6, 0x4800
	s_addc_u32 s19, s7, 0
	s_add_u32 s20, s6, 0x4900
	s_addc_u32 s21, s7, 0
	s_add_u32 s22, s6, 0x4a00
	s_addc_u32 s23, s7, 0
	s_add_u32 s24, s6, 0x4b00
	s_addc_u32 s25, s7, 0
	s_add_u32 s26, s6, 0x4c00
	s_addc_u32 s27, s7, 0
	s_add_u32 s28, s6, 0x4d00
	s_addc_u32 s29, s7, 0
	s_add_u32 s30, s6, 0x4e00
	s_addc_u32 s31, s7, 0
	s_add_u32 s36, s6, 0x4f00
	s_addc_u32 s37, s7, 0
	s_add_u32 s40, s6, 0x5000
	s_addc_u32 s41, s7, 0
	s_add_u32 s42, s6, 0x5100
	s_addc_u32 s43, s7, 0
	s_add_u32 s44, s6, 0x5200
	s_addc_u32 s45, s7, 0
	s_waitcnt lgkmcnt(0)
	s_mul_i32 s2, s2, s65
	s_add_u32 s46, s6, 0x5300
	s_mul_i32 s2, s2, s3
	s_addc_u32 s47, s7, 0
	s_mov_b32 s3, 1
	v_mov_b32_e32 v17, 0
	s_branch .LBB0_207

.LBB0_234:
	s_or_b64 exec, exec, s[10:11]
	s_waitcnt vmcnt(0)
	s_waitcnt vmcnt(0)

.LBB0_252:
	s_or_b64 exec, exec, s[6:7]
	s_mov_b64 s[6:7], exec
	v_mbcnt_lo_u32_b32 v1, s6, 0
	v_mbcnt_hi_u32_b32 v1, s7, v1
	s_mov_b32 s11, 0
	v_cmp_eq_u32_e32 vcc, 0, v1
	s_waitcnt vmcnt(0)
	s_and_saveexec_b64 s[8:9], vcc
	s_cbranch_execz .LBB0_254
	s_add_i32 s10, s26, 0x900
	s_lshl_b64 s[10:11], s[10:11], 2
	s_add_u32 s2, s2, s10
	s_addc_u32 s3, s3, s11
	s_bcnt1_i32_b64 s6, s[6:7]
	v_mov_b32_e32 v1, 0
	v_mov_b32_e32 v2, s6
	global_atomic_add v1, v2, s[2:3]

.Lgb0_slow:
	s_mov_b64 s[8:9], s[0:1]
	s_mov_b32 s40, s90
	s_waitcnt vmcnt(0)
	s_barrier
	s_mov_b64 s[4:5], exec
	v_readlane_b32 s10, v255, 5
	v_readlane_b32 s11, v255, 6
	s_and_b64 s[10:11], s[4:5], s[10:11]
	s_mov_b64 exec, s[10:11]
	s_cbranch_execz .LBB0_337
	buffer_inv sc1
	v_readlane_b32 s10, v255, 16
	s_load_dwordx2 s[8:9], s[8:9], 0xd8
	s_waitcnt vmcnt(0) expcnt(0) lgkmcnt(0)
	v_mov_b32_e32 v2, s10
	ds_read_b32 v5, v2
	v_readlane_b32 s10, v255, 17
	s_waitcnt lgkmcnt(0)
	v_cmp_ne_u32_e32 vcc, 0, v5
	v_mov_b32_e32 v2, s10
	ds_read_b32 v4, v2
	s_cbranch_vccnz .LBB0_301
	v_readlane_b32 s10, v255, 2
	v_readlane_b32 s11, v255, 3
	s_load_dwordx2 s[18:19], s[10:11], 0x4
	s_add_u32 s10, s8, 0x4200
	s_addc_u32 s11, s9, 0
	s_add_u32 s14, s8, 0x4400
	s_addc_u32 s15, s9, 0
	s_waitcnt lgkmcnt(0)
	s_mul_i32 s35, s18, s65
	s_add_u32 s18, s8, 0x4500
	s_mul_i32 s35, s35, s19
	s_addc_u32 s19, s9, 0
	s_add_u32 s20, s8, 0x4600
	s_addc_u32 s21, s9, 0
	s_add_u32 s22, s8, 0x4700
	s_addc_u32 s23, s9, 0
	s_add_u32 s24, s8, 0x4800
	s_addc_u32 s25, s9, 0
	s_add_u32 s26, s8, 0x4900
	s_addc_u32 s27, s9, 0
	s_add_u32 s28, s8, 0x4a00
	s_addc_u32 s29, s9, 0
	s_add_u32 s30, s8, 0x4b00
	s_addc_u32 s31, s9, 0
	s_add_u32 s36, s8, 0x4c00
	s_addc_u32 s37, s9, 0
	s_add_u32 s44, s8, 0x4d00
	s_addc_u32 s45, s9, 0
	s_add_u32 s46, s8, 0x4e00
	s_addc_u32 s47, s9, 0
	s_add_u32 s72, s8, 0x4f00
	s_addc_u32 s73, s9, 0
	s_add_u32 s74, s8, 0x5000
	s_addc_u32 s75, s9, 0
	s_add_u32 s76, s8, 0x5100
	s_addc_u32 s77, s9, 0
	s_add_u32 s78, s8, 0x5200
	s_addc_u32 s79, s9, 0
	s_add_u32 s82, s8, 0x5300
	s_addc_u32 s83, s9, 0
	s_mov_b32 s48, 1
	s_branch .LBB0_289

.LBB0_316:
	s_or_b64 exec, exec, s[14:15]
	s_waitcnt vmcnt(0)
	s_waitcnt vmcnt(0)

.LBB0_334:
	s_or_b64 exec, exec, s[8:9]
	s_mov_b64 s[8:9], exec
	v_mbcnt_lo_u32_b32 v2, s8, 0
	v_mbcnt_hi_u32_b32 v2, s9, v2
	v_cmp_eq_u32_e32 vcc, 0, v2
	s_waitcnt vmcnt(0)
	s_and_saveexec_b64 s[10:11], vcc
	s_cbranch_execz .LBB0_336
	s_add_i32 s40, s37, 0x900
	s_lshl_b64 s[14:15], s[40:41], 2
	s_add_u32 s14, s35, s14
	s_addc_u32 s15, s36, s15
	s_bcnt1_i32_b64 s8, s[8:9]
	v_mov_b32_e32 v2, s8
	global_atomic_add v3, v2, s[14:15]

.Lgb1_slow:
	s_mov_b64 s[8:9], s[0:1]
	s_mov_b32 s40, s90
	s_waitcnt vmcnt(0)
	s_waitcnt vmcnt(0)
	s_barrier
	s_mov_b64 s[4:5], exec
	v_readlane_b32 s10, v255, 5
	v_readlane_b32 s11, v255, 6
	s_and_b64 s[10:11], s[4:5], s[10:11]
	s_mov_b64 exec, s[10:11]
	s_cbranch_execz .LBB0_412
	buffer_inv sc1
	v_readlane_b32 s10, v255, 16
	s_load_dwordx2 s[8:9], s[8:9], 0xd8
	s_waitcnt vmcnt(0) expcnt(0) lgkmcnt(0)
	v_mov_b32_e32 v2, s10
	ds_read_b32 v5, v2
	v_readlane_b32 s10, v255, 17
	s_waitcnt lgkmcnt(0)
	v_cmp_ne_u32_e32 vcc, 0, v5
	v_mov_b32_e32 v2, s10
	ds_read_b32 v4, v2
	s_cbranch_vccnz .LBB0_376
	v_readlane_b32 s10, v255, 2
	v_readlane_b32 s11, v255, 3
	s_load_dwordx2 s[18:19], s[10:11], 0x4
	s_add_u32 s10, s8, 0x4200
	s_addc_u32 s11, s9, 0
	s_add_u32 s14, s8, 0x4400
	s_addc_u32 s15, s9, 0
	s_waitcnt lgkmcnt(0)
	s_mul_i32 s35, s18, s65
	s_add_u32 s18, s8, 0x4500
	s_mul_i32 s35, s35, s19
	s_addc_u32 s19, s9, 0
	s_add_u32 s20, s8, 0x4600
	s_addc_u32 s21, s9, 0
	s_add_u32 s22, s8, 0x4700
	s_addc_u32 s23, s9, 0
	s_add_u32 s24, s8, 0x4800
	s_addc_u32 s25, s9, 0
	s_add_u32 s26, s8, 0x4900
	s_addc_u32 s27, s9, 0
	s_add_u32 s28, s8, 0x4a00
	s_addc_u32 s29, s9, 0
	s_add_u32 s30, s8, 0x4b00
	s_addc_u32 s31, s9, 0
	s_add_u32 s36, s8, 0x4c00
	s_addc_u32 s37, s9, 0
	s_add_u32 s44, s8, 0x4d00
	s_addc_u32 s45, s9, 0
	s_add_u32 s46, s8, 0x4e00
	s_addc_u32 s47, s9, 0
	s_add_u32 s72, s8, 0x4f00
	s_addc_u32 s73, s9, 0
	s_add_u32 s74, s8, 0x5000
	s_addc_u32 s75, s9, 0
	s_add_u32 s76, s8, 0x5100
	s_addc_u32 s77, s9, 0
	s_add_u32 s78, s8, 0x5200
	s_addc_u32 s79, s9, 0
	s_add_u32 s82, s8, 0x5300
	s_addc_u32 s83, s9, 0
	s_mov_b32 s48, 1
	s_branch .LBB0_364

.Lgb2_slow:
	s_mov_b64 s[8:9], s[0:1]
	s_mov_b32 s40, s90
	s_waitcnt vmcnt(0)
	s_waitcnt vmcnt(0)
	s_barrier
	s_mov_b64 s[4:5], exec
	v_readlane_b32 s10, v255, 5
	v_readlane_b32 s11, v255, 6
	s_and_b64 s[10:11], s[4:5], s[10:11]
	s_mov_b64 exec, s[10:11]
	s_cbranch_execz .LBB0_495
	buffer_inv sc1
	v_readlane_b32 s10, v255, 16
	s_load_dwordx2 s[8:9], s[8:9], 0xd8
	s_waitcnt vmcnt(0) expcnt(0) lgkmcnt(0)
	v_mov_b32_e32 v2, s10
	ds_read_b32 v5, v2
	v_readlane_b32 s10, v255, 17
	s_waitcnt lgkmcnt(0)
	v_cmp_ne_u32_e32 vcc, 0, v5
	v_mov_b32_e32 v2, s10
	ds_read_b32 v4, v2
	s_cbranch_vccnz .LBB0_459
	v_readlane_b32 s10, v255, 2
	v_readlane_b32 s11, v255, 3
	s_load_dwordx2 s[18:19], s[10:11], 0x4
	s_add_u32 s10, s8, 0x4200
	s_addc_u32 s11, s9, 0
	s_add_u32 s14, s8, 0x4400
	s_addc_u32 s15, s9, 0
	s_waitcnt lgkmcnt(0)
	s_mul_i32 s17, s18, s65
	s_add_u32 s18, s8, 0x4500
	s_mul_i32 s17, s17, s19
	s_addc_u32 s19, s9, 0
	s_add_u32 s20, s8, 0x4600
	s_addc_u32 s21, s9, 0
	s_add_u32 s22, s8, 0x4700
	s_addc_u32 s23, s9, 0
	s_add_u32 s24, s8, 0x4800
	s_addc_u32 s25, s9, 0
	s_add_u32 s26, s8, 0x4900
	s_addc_u32 s27, s9, 0
	s_add_u32 s28, s8, 0x4a00
	s_addc_u32 s29, s9, 0
	s_add_u32 s30, s8, 0x4b00
	s_addc_u32 s31, s9, 0
	s_add_u32 s36, s8, 0x4c00
	s_addc_u32 s37, s9, 0
	s_add_u32 s44, s8, 0x4d00
	s_addc_u32 s45, s9, 0
	s_add_u32 s46, s8, 0x4e00
	s_addc_u32 s47, s9, 0
	s_add_u32 s72, s8, 0x4f00
	s_addc_u32 s73, s9, 0
	s_add_u32 s74, s8, 0x5000
	s_addc_u32 s75, s9, 0
	s_add_u32 s76, s8, 0x5100
	s_addc_u32 s77, s9, 0
	s_add_u32 s78, s8, 0x5200
	s_addc_u32 s79, s9, 0
	s_add_u32 s82, s8, 0x5300
	s_addc_u32 s83, s9, 0
	s_mov_b32 s35, 1
	s_branch .LBB0_447

.LBB0_492:
	s_or_b64 exec, exec, s[8:9]
	s_mov_b64 s[8:9], exec
	v_mbcnt_lo_u32_b32 v2, s8, 0
	v_mbcnt_hi_u32_b32 v2, s9, v2
	v_cmp_eq_u32_e32 vcc, 0, v2
	s_waitcnt vmcnt(0)
	s_and_saveexec_b64 s[10:11], vcc
	s_cbranch_execz .LBB0_494
	s_add_i32 s40, s36, 0x900
	s_lshl_b64 s[14:15], s[40:41], 2
	s_add_u32 s14, s17, s14
	s_addc_u32 s15, s35, s15
	s_bcnt1_i32_b64 s8, s[8:9]
	v_mov_b32_e32 v2, s8
	global_atomic_add v3, v2, s[14:15]

.LBB0_507:
	s_or_b64 exec, exec, s[6:7]
	v_readlane_b32 s4, v255, 15
	s_add_i32 s17, s4, 4
	v_readlane_b32 s4, v255, 0
	v_readlane_b32 s5, v255, 1
	s_cmp_ge_i32 s17, s5
	s_cbranch_scc1 .LBB0_562
	s_mov_b64 s[6:7], s[0:1]
	s_mov_b32 s34, s90
	s_waitcnt vmcnt(0)
	s_waitcnt vmcnt(0)
	s_barrier
	s_mov_b64 s[4:5], exec
	v_readlane_b32 s8, v255, 5
	v_readlane_b32 s9, v255, 6
	s_and_b64 s[8:9], s[4:5], s[8:9]
	s_mov_b64 exec, s[8:9]
	s_cbranch_execz .LBB0_561
	buffer_inv sc1
	v_readlane_b32 s8, v255, 16
	s_load_dwordx2 s[6:7], s[6:7], 0xd8
	s_waitcnt vmcnt(0) expcnt(0) lgkmcnt(0)
	v_mov_b32_e32 v2, s8
	ds_read_b32 v5, v2
	v_readlane_b32 s8, v255, 17
	s_waitcnt lgkmcnt(0)
	v_cmp_ne_u32_e32 vcc, 0, v5
	v_mov_b32_e32 v2, s8
	ds_read_b32 v4, v2
	s_cbranch_vccnz .LBB0_525
	v_readlane_b32 s8, v255, 2
	v_readlane_b32 s9, v255, 3
	s_load_dwordx2 s[14:15], s[8:9], 0x4
	s_add_u32 s8, s6, 0x4200
	s_addc_u32 s9, s7, 0
	s_add_u32 s10, s6, 0x4400
	s_addc_u32 s11, s7, 0
	s_waitcnt lgkmcnt(0)
	s_mul_i32 s35, s14, s65
	s_add_u32 s14, s6, 0x4500
	s_mul_i32 s35, s35, s15
	s_addc_u32 s15, s7, 0
	s_add_u32 s18, s6, 0x4600
	s_addc_u32 s19, s7, 0
	s_add_u32 s20, s6, 0x4700
	s_addc_u32 s21, s7, 0
	s_add_u32 s22, s6, 0x4800
	s_addc_u32 s23, s7, 0
	s_add_u32 s24, s6, 0x4900
	s_addc_u32 s25, s7, 0
	s_add_u32 s26, s6, 0x4a00
	s_addc_u32 s27, s7, 0
	s_add_u32 s28, s6, 0x4b00
	s_addc_u32 s29, s7, 0
	s_add_u32 s30, s6, 0x4c00
	s_addc_u32 s31, s7, 0
	s_add_u32 s36, s6, 0x4d00
	s_addc_u32 s37, s7, 0
	s_add_u32 s44, s6, 0x4e00
	s_addc_u32 s45, s7, 0
	s_add_u32 s46, s6, 0x4f00
	s_addc_u32 s47, s7, 0
	s_add_u32 s72, s6, 0x5000
	s_addc_u32 s73, s7, 0
	s_add_u32 s74, s6, 0x5100
	s_addc_u32 s75, s7, 0
	s_add_u32 s76, s6, 0x5200
	s_addc_u32 s77, s7, 0
	s_add_u32 s78, s6, 0x5300
	s_addc_u32 s79, s7, 0
	s_mov_b32 s40, 1
	s_branch .LBB0_512

.LBB0_558:
	s_or_b64 exec, exec, s[6:7]
	s_mov_b64 s[6:7], exec
	v_mbcnt_lo_u32_b32 v2, s6, 0
	v_mbcnt_hi_u32_b32 v2, s7, v2
	v_cmp_eq_u32_e32 vcc, 0, v2
	s_waitcnt vmcnt(0)
	s_and_saveexec_b64 s[8:9], vcc
	s_cbranch_execz .LBB0_560
	s_add_i32 s40, s34, 0x900
	s_lshl_b64 s[10:11], s[40:41], 2
	s_add_u32 s10, s30, s10
	s_addc_u32 s11, s31, s11
	s_bcnt1_i32_b64 s6, s[6:7]
	v_mov_b32_e32 v2, s6
	global_atomic_add v3, v2, s[10:11]

.Lgb4_slow:
	s_mov_b64 s[6:7], s[0:1]
	s_mov_b32 s34, s90
	s_waitcnt vmcnt(0)
	s_barrier
	s_mov_b64 s[4:5], exec
	v_readlane_b32 s8, v255, 5
	v_readlane_b32 s9, v255, 6
	s_and_b64 s[8:9], s[4:5], s[8:9]
	s_mov_b64 exec, s[8:9]
	s_cbranch_execz .LBB0_778
	buffer_inv sc1
	v_readlane_b32 s8, v255, 16
	s_load_dwordx2 s[6:7], s[6:7], 0xd8
	s_waitcnt vmcnt(0) expcnt(0) lgkmcnt(0)
	v_mov_b32_e32 v2, s8
	ds_read_b32 v5, v2
	v_readlane_b32 s8, v255, 17
	s_waitcnt lgkmcnt(0)
	v_cmp_ne_u32_e32 vcc, 0, v5
	v_mov_b32_e32 v2, s8
	ds_read_b32 v4, v2
	s_cbranch_vccnz .LBB0_742
	v_readlane_b32 s8, v255, 2
	v_readlane_b32 s9, v255, 3
	s_load_dwordx2 s[14:15], s[8:9], 0x4
	s_add_u32 s8, s6, 0x4200
	s_addc_u32 s9, s7, 0
	s_add_u32 s10, s6, 0x4400
	s_addc_u32 s11, s7, 0
	s_waitcnt lgkmcnt(0)
	s_mul_i32 s35, s14, s65
	s_add_u32 s14, s6, 0x4500
	s_mul_i32 s35, s35, s15
	s_addc_u32 s15, s7, 0
	s_add_u32 s18, s6, 0x4600
	s_addc_u32 s19, s7, 0
	s_add_u32 s20, s6, 0x4700
	s_addc_u32 s21, s7, 0
	s_add_u32 s22, s6, 0x4800
	s_addc_u32 s23, s7, 0
	s_add_u32 s24, s6, 0x4900
	s_addc_u32 s25, s7, 0
	s_add_u32 s26, s6, 0x4a00
	s_addc_u32 s27, s7, 0
	s_add_u32 s28, s6, 0x4b00
	s_addc_u32 s29, s7, 0
	s_add_u32 s30, s6, 0x4c00
	s_addc_u32 s31, s7, 0
	s_add_u32 s36, s6, 0x4d00
	s_addc_u32 s37, s7, 0
	s_add_u32 s44, s6, 0x4e00
	s_addc_u32 s45, s7, 0
	s_add_u32 s46, s6, 0x4f00
	s_addc_u32 s47, s7, 0
	s_add_u32 s72, s6, 0x5000
	s_addc_u32 s73, s7, 0
	s_add_u32 s74, s6, 0x5100
	s_addc_u32 s75, s7, 0
	s_add_u32 s76, s6, 0x5200
	s_addc_u32 s77, s7, 0
	s_add_u32 s78, s6, 0x5300
	s_addc_u32 s79, s7, 0
	s_mov_b32 s40, 1
	s_branch .LBB0_730

.LBB0_813:
	s_or_b64 exec, exec, s[6:7]
	v_readlane_b32 s4, v255, 15
	s_add_i32 s17, s4, 6
	v_readlane_b32 s4, v255, 0
	v_readlane_b32 s5, v255, 1
	s_cmp_ge_i32 s17, s5
	s_cbranch_scc1 .LBB0_867
	s_mov_b64 s[6:7], s[0:1]
	s_mov_b32 s34, s90
	s_waitcnt vmcnt(0)
	s_waitcnt vmcnt(0) lgkmcnt(0)
	s_barrier
	s_mov_b64 s[4:5], exec
	v_readlane_b32 s8, v255, 5
	v_readlane_b32 s9, v255, 6
	s_and_b64 s[8:9], s[4:5], s[8:9]
	s_mov_b64 exec, s[8:9]
	s_cbranch_execz .LBB0_866
	buffer_inv sc1
	v_readlane_b32 s8, v255, 16
	s_load_dwordx2 s[6:7], s[6:7], 0xd8
	s_waitcnt vmcnt(0) expcnt(0) lgkmcnt(0)
	v_mov_b32_e32 v2, s8
	ds_read_b32 v5, v2
	v_readlane_b32 s8, v255, 17
	s_waitcnt lgkmcnt(0)
	v_cmp_ne_u32_e32 vcc, 0, v5
	v_mov_b32_e32 v2, s8
	ds_read_b32 v4, v2
	s_cbranch_vccnz .LBB0_830
	v_readlane_b32 s8, v255, 2
	v_readlane_b32 s9, v255, 3
	s_load_dwordx2 s[14:15], s[8:9], 0x4
	s_add_u32 s8, s6, 0x4200
	s_addc_u32 s9, s7, 0
	s_add_u32 s10, s6, 0x4400
	s_addc_u32 s11, s7, 0
	s_waitcnt lgkmcnt(0)
	s_mul_i32 s35, s14, s65
	s_add_u32 s14, s6, 0x4500
	s_mul_i32 s35, s35, s15
	s_addc_u32 s15, s7, 0
	s_add_u32 s18, s6, 0x4600
	s_addc_u32 s19, s7, 0
	s_add_u32 s20, s6, 0x4700
	s_addc_u32 s21, s7, 0
	s_add_u32 s22, s6, 0x4800
	s_addc_u32 s23, s7, 0
	s_add_u32 s24, s6, 0x4900
	s_addc_u32 s25, s7, 0
	s_add_u32 s26, s6, 0x4a00
	s_addc_u32 s27, s7, 0
	s_add_u32 s28, s6, 0x4b00
	s_addc_u32 s29, s7, 0
	s_add_u32 s30, s6, 0x4c00
	s_addc_u32 s31, s7, 0
	s_add_u32 s36, s6, 0x4d00
	s_addc_u32 s37, s7, 0
	s_add_u32 s44, s6, 0x4e00
	s_addc_u32 s45, s7, 0
	s_add_u32 s46, s6, 0x4f00
	s_addc_u32 s47, s7, 0
	s_add_u32 s72, s6, 0x5000
	s_addc_u32 s73, s7, 0
	s_add_u32 s74, s6, 0x5100
	s_addc_u32 s75, s7, 0
	s_add_u32 s76, s6, 0x5200
	s_addc_u32 s77, s7, 0
	s_add_u32 s78, s6, 0x5300
	s_addc_u32 s79, s7, 0
	s_mov_b32 s40, 1
	s_branch .LBB0_818

.LBB0_953:
	v_readlane_b32 s4, v255, 15
	s_add_i32 s17, s4, 7
	v_readlane_b32 s4, v255, 0
	v_readlane_b32 s5, v255, 1
	s_cmp_ge_i32 s17, s5
	s_cbranch_scc1 .LBB0_1007
	s_mov_b64 s[6:7], s[0:1]
	s_mov_b32 s34, s90
	s_waitcnt vmcnt(0)
	s_waitcnt vmcnt(0) lgkmcnt(0)
	s_barrier
	s_mov_b64 s[4:5], exec
	v_readlane_b32 s8, v255, 5
	v_readlane_b32 s9, v255, 6
	s_and_b64 s[8:9], s[4:5], s[8:9]
	s_mov_b64 exec, s[8:9]
	s_cbranch_execz .LBB0_1006
	buffer_inv sc1
	v_readlane_b32 s8, v255, 16
	s_load_dwordx2 s[6:7], s[6:7], 0xd8
	s_waitcnt vmcnt(0) expcnt(0) lgkmcnt(0)
	v_mov_b32_e32 v2, s8
	ds_read_b32 v5, v2
	v_readlane_b32 s8, v255, 17
	s_waitcnt lgkmcnt(0)
	v_cmp_ne_u32_e32 vcc, 0, v5
	v_mov_b32_e32 v2, s8
	ds_read_b32 v4, v2
	s_cbranch_vccnz .LBB0_970
	v_readlane_b32 s8, v255, 2
	v_readlane_b32 s9, v255, 3
	s_load_dwordx2 s[14:15], s[8:9], 0x4
	s_add_u32 s8, s6, 0x4200
	s_addc_u32 s9, s7, 0
	s_add_u32 s10, s6, 0x4400
	s_addc_u32 s11, s7, 0
	s_waitcnt lgkmcnt(0)
	s_mul_i32 s35, s14, s65
	s_add_u32 s14, s6, 0x4500
	s_mul_i32 s35, s35, s15
	s_addc_u32 s15, s7, 0
	s_add_u32 s18, s6, 0x4600
	s_addc_u32 s19, s7, 0
	s_add_u32 s20, s6, 0x4700
	s_addc_u32 s21, s7, 0
	s_add_u32 s22, s6, 0x4800
	s_addc_u32 s23, s7, 0
	s_add_u32 s24, s6, 0x4900
	s_addc_u32 s25, s7, 0
	s_add_u32 s26, s6, 0x4a00
	s_addc_u32 s27, s7, 0
	s_add_u32 s28, s6, 0x4b00
	s_addc_u32 s29, s7, 0
	s_add_u32 s30, s6, 0x4c00
	s_addc_u32 s31, s7, 0
	s_add_u32 s36, s6, 0x4d00
	s_addc_u32 s37, s7, 0
	s_add_u32 s44, s6, 0x4e00
	s_addc_u32 s45, s7, 0
	s_add_u32 s46, s6, 0x4f00
	s_addc_u32 s47, s7, 0
	s_add_u32 s72, s6, 0x5000
	s_addc_u32 s73, s7, 0
	s_add_u32 s74, s6, 0x5100
	s_addc_u32 s75, s7, 0
	s_add_u32 s76, s6, 0x5200
	s_addc_u32 s77, s7, 0
	s_add_u32 s78, s6, 0x5300
	s_addc_u32 s79, s7, 0
	s_mov_b32 s40, 1
	s_branch .LBB0_958

.LBB0_1137:
	v_readlane_b32 s4, v255, 15
	s_add_i32 s17, s4, 8
	v_readlane_b32 s4, v255, 0
	v_readlane_b32 s5, v255, 1
	s_cmp_ge_i32 s17, s5
	s_barrier
	s_barrier
	s_cbranch_scc1 .LBB0_1191
	s_mov_b64 s[6:7], s[0:1]
	s_mov_b32 s34, s90
	s_waitcnt vmcnt(0)
	s_barrier
	s_mov_b64 s[4:5], exec
	v_readlane_b32 s8, v255, 5
	v_readlane_b32 s9, v255, 6
	s_and_b64 s[8:9], s[4:5], s[8:9]
	s_mov_b64 exec, s[8:9]
	s_cbranch_execz .LBB0_1190
	buffer_inv sc1
	v_readlane_b32 s8, v255, 16
	s_load_dwordx2 s[6:7], s[6:7], 0xd8
	s_waitcnt vmcnt(0) expcnt(0) lgkmcnt(0)
	v_mov_b32_e32 v2, s8
	ds_read_b32 v5, v2
	v_readlane_b32 s8, v255, 17
	s_waitcnt lgkmcnt(0)
	v_cmp_ne_u32_e32 vcc, 0, v5
	v_mov_b32_e32 v2, s8
	ds_read_b32 v4, v2
	s_cbranch_vccnz .LBB0_1154
	v_readlane_b32 s8, v255, 2
	v_readlane_b32 s9, v255, 3
	s_load_dwordx2 s[14:15], s[8:9], 0x4
	s_add_u32 s8, s6, 0x4200
	s_addc_u32 s9, s7, 0
	s_add_u32 s10, s6, 0x4400
	s_addc_u32 s11, s7, 0
	s_waitcnt lgkmcnt(0)
	s_mul_i32 s35, s14, s65
	s_add_u32 s14, s6, 0x4500
	s_mul_i32 s35, s35, s15
	s_addc_u32 s15, s7, 0
	s_add_u32 s18, s6, 0x4600
	s_addc_u32 s19, s7, 0
	s_add_u32 s20, s6, 0x4700
	s_addc_u32 s21, s7, 0
	s_add_u32 s22, s6, 0x4800
	s_addc_u32 s23, s7, 0
	s_add_u32 s24, s6, 0x4900
	s_addc_u32 s25, s7, 0
	s_add_u32 s26, s6, 0x4a00
	s_addc_u32 s27, s7, 0
	s_add_u32 s28, s6, 0x4b00
	s_addc_u32 s29, s7, 0
	s_add_u32 s30, s6, 0x4c00
	s_addc_u32 s31, s7, 0
	s_add_u32 s36, s6, 0x4d00
	s_addc_u32 s37, s7, 0
	s_add_u32 s44, s6, 0x4e00
	s_addc_u32 s45, s7, 0
	s_add_u32 s46, s6, 0x4f00
	s_addc_u32 s47, s7, 0
	s_add_u32 s72, s6, 0x5000
	s_addc_u32 s73, s7, 0
	s_add_u32 s74, s6, 0x5100
	s_addc_u32 s75, s7, 0
	s_add_u32 s76, s6, 0x5200
	s_addc_u32 s77, s7, 0
	s_add_u32 s78, s6, 0x5300
	s_addc_u32 s79, s7, 0
	s_mov_b32 s40, 1
	s_branch .LBB0_1142

.LBB0_1222:
	buffer_inv sc1
	v_readlane_b32 s8, v255, 16
	s_load_dwordx2 s[6:7], s[6:7], 0xd8
	s_waitcnt vmcnt(0) expcnt(0) lgkmcnt(0)
	v_mov_b32_e32 v2, s8
	ds_read_b32 v5, v2
	v_readlane_b32 s8, v255, 17
	s_waitcnt lgkmcnt(0)
	v_cmp_ne_u32_e32 vcc, 0, v5
	v_mov_b32_e32 v2, s8
	ds_read_b32 v4, v2
	s_cbranch_vccnz .LBB0_1237
	v_readlane_b32 s8, v255, 2
	v_readlane_b32 s9, v255, 3
	s_load_dwordx2 s[14:15], s[8:9], 0x4
	s_add_u32 s8, s6, 0x4200
	s_addc_u32 s9, s7, 0
	s_add_u32 s10, s6, 0x4400
	s_addc_u32 s11, s7, 0
	s_waitcnt lgkmcnt(0)
	s_mul_i32 s35, s14, s65
	s_add_u32 s14, s6, 0x4500
	s_mul_i32 s35, s35, s15
	s_addc_u32 s15, s7, 0
	s_add_u32 s18, s6, 0x4600
	s_addc_u32 s19, s7, 0
	s_add_u32 s20, s6, 0x4700
	s_addc_u32 s21, s7, 0
	s_add_u32 s22, s6, 0x4800
	s_addc_u32 s23, s7, 0
	s_add_u32 s24, s6, 0x4900
	s_addc_u32 s25, s7, 0
	s_add_u32 s26, s6, 0x4a00
	s_addc_u32 s27, s7, 0
	s_add_u32 s28, s6, 0x4b00
	s_addc_u32 s29, s7, 0
	s_add_u32 s30, s6, 0x4c00
	s_addc_u32 s31, s7, 0
	s_add_u32 s36, s6, 0x4d00
	s_addc_u32 s37, s7, 0
	s_add_u32 s44, s6, 0x4e00
	s_addc_u32 s45, s7, 0
	s_add_u32 s46, s6, 0x4f00
	s_addc_u32 s47, s7, 0
	s_add_u32 s72, s6, 0x5000
	s_addc_u32 s73, s7, 0
	s_add_u32 s74, s6, 0x5100
	s_addc_u32 s75, s7, 0
	s_add_u32 s76, s6, 0x5200
	s_addc_u32 s77, s7, 0
	s_add_u32 s78, s6, 0x5300
	s_addc_u32 s79, s7, 0
	s_mov_b32 s40, 1
	s_branch .LBB0_1225

.LBB0_1270:
	s_or_b64 exec, exec, s[6:7]
	s_mov_b64 s[6:7], exec
	v_mbcnt_lo_u32_b32 v2, s6, 0
	v_mbcnt_hi_u32_b32 v2, s7, v2
	v_cmp_eq_u32_e32 vcc, 0, v2
	s_waitcnt vmcnt(0)
	s_and_saveexec_b64 s[8:9], vcc
	s_cbranch_execnz .LBB0_1271
	s_getpc_b64 s[98:99]

.LBB0_1278:
	s_or_b64 exec, exec, s[6:7]
	v_readlane_b32 s2, v255, 15
	v_readlane_b32 s4, v255, 0
	s_add_i32 s2, s2, 1
	v_readlane_b32 s5, v255, 1
	s_cmp_ge_i32 s2, s5
	s_cbranch_scc1 .LBB0_1332
	s_waitcnt vmcnt(0)
	s_waitcnt vmcnt(0) lgkmcnt(0)
	s_barrier
	s_mov_b64 s[2:3], exec
	v_readlane_b32 s4, v255, 5
	v_readlane_b32 s5, v255, 6
	s_and_b64 s[4:5], s[2:3], s[4:5]
	s_mov_b64 exec, s[4:5]
	s_cbranch_execz .LBB0_1331
	buffer_inv sc1
	s_add_i32 s4, 0, 0x20000
	v_mov_b32_e32 v0, s4
	s_load_dwordx2 s[0:1], s[0:1], 0xd8
	s_waitcnt vmcnt(0) expcnt(0) lgkmcnt(0)
	ds_read_b32 v2, v0
	s_add_i32 s4, 0, 0x20004
	v_mov_b32_e32 v0, s4
	ds_read_b32 v0, v0
	s_waitcnt lgkmcnt(1)
	v_cmp_ne_u32_e32 vcc, 0, v2
	s_cbranch_vccnz .LBB0_1295
	v_readlane_b32 s4, v255, 2
	v_readlane_b32 s5, v255, 3
	s_load_dwordx2 s[8:9], s[4:5], 0x4
	s_add_u32 s4, s0, 0x4200
	s_addc_u32 s5, s1, 0
	s_add_u32 s6, s0, 0x4400
	s_addc_u32 s7, s1, 0
	s_waitcnt lgkmcnt(0)
	s_mul_i32 s33, s8, s65
	s_add_u32 s8, s0, 0x4500
	s_mul_i32 s33, s33, s9
	s_addc_u32 s9, s1, 0
	s_add_u32 s10, s0, 0x4600
	s_addc_u32 s11, s1, 0
	s_add_u32 s12, s0, 0x4700
	s_addc_u32 s13, s1, 0
	s_add_u32 s14, s0, 0x4800
	s_addc_u32 s15, s1, 0
	s_add_u32 s16, s0, 0x4900
	s_addc_u32 s17, s1, 0
	s_add_u32 s18, s0, 0x4a00
	s_addc_u32 s19, s1, 0
	s_add_u32 s20, s0, 0x4b00
	s_addc_u32 s21, s1, 0
	s_add_u32 s22, s0, 0x4c00
	s_addc_u32 s23, s1, 0
	s_add_u32 s24, s0, 0x4d00
	s_addc_u32 s25, s1, 0
	s_add_u32 s26, s0, 0x4e00
	s_addc_u32 s27, s1, 0
	s_add_u32 s28, s0, 0x4f00
	s_addc_u32 s29, s1, 0
	s_add_u32 s30, s0, 0x5000
	s_addc_u32 s31, s1, 0
	s_add_u32 s34, s0, 0x5100
	s_addc_u32 s35, s1, 0
	s_add_u32 s36, s0, 0x5200
	s_addc_u32 s37, s1, 0
	s_add_u32 s38, s0, 0x5300
	s_addc_u32 s39, s1, 0
	s_mov_b32 s46, 1
	v_mov_b32_e32 v16, 0
	s_branch .LBB0_1283

.LBB0_1310:
	s_or_b64 exec, exec, s[6:7]
	s_waitcnt vmcnt(0)
	s_waitcnt vmcnt(0)

.LBB0_1328:
	s_or_b64 exec, exec, s[0:1]
	s_mov_b64 s[0:1], exec
	v_mbcnt_lo_u32_b32 v0, s0, 0
	v_mbcnt_hi_u32_b32 v0, s1, v0
	s_mov_b32 s7, 0
	v_cmp_eq_u32_e32 vcc, 0, v0
	s_waitcnt vmcnt(0)
	s_and_saveexec_b64 s[4:5], vcc
	s_cbranch_execz .LBB0_1330
	s_add_i32 s6, s24, 0x900
	s_lshl_b64 s[6:7], s[6:7], 2
	s_add_u32 s6, s22, s6
	s_addc_u32 s7, s23, s7
	s_bcnt1_i32_b64 s0, s[0:1]
	v_mov_b32_e32 v0, 0
	v_mov_b32_e32 v1, s0
	global_atomic_add v0, v1, s[6:7]
